# rebalanced tail-convert table over 10 GEMM-tail slots plus small pre-loop slot; pipelined convert loop
# speedup vs baseline: 1.0101x; 1.0101x over previous
; __device__ __forceinline__ unsigned pack2bf(float lo, float hi) { unsigned r; asm("v_cvt_pk_bf16_f32 %0, %1, %2" : "=v"(r) : "v"(lo), "v"(hi)); return r; }
; __device__ __forceinline__ void cvt_decode(PP p, int tile, const float*& src  , int& ld, bf16_t*& dst, int& K, int& k0, int& n0, int n4) {
;   unsigned char* ws = p->ws;
;   src = nullptr;
;   if (tile < NT_WGU) {
;     const int li = tile / (32 * 88), r = tile % (32 * 88), kt = r / 88, ntile = r % 88;
;     K = D; k0 = kt * 64; n0 = ntile * 128; ld = DFF; dst = (bf16_t*)(ws + WS_WGU) + (size_t)li * 2 * DFF * D;
;     const int pn = n0 / 256, bj = (n0 / 128) & 1;
;     const float* base = (bj ? p->ffn_wu : p->ffn_wg) + (size_t)li * D * DFF;
;     src = base + (size_t)k0 * ld + pn * 128 + n4 * 4;
;   } else if (tile < NT_WGU + NT_WD) {
;     const int t2 = tile - NT_WGU; const int li = t2 / (88 * 16), r = t2 % (88 * 16), kt = r / 16, ntile = r % 16;
;     K = DFF; k0 = kt * 64; n0 = ntile * 128; ld = D; dst = (bf16_t*)(ws + WS_WD) + (size_t)li * D * DFF;
;     src = p->ffn_wd + (size_t)li * DFF * D + (size_t)k0 * ld + n0 + n4 * 4;
; __device__ void phase_convert(PP p, unsigned char* smem) {
;     ...
; #pragma unroll
;     for (int i = 0; i < 4; ++i) {
;       float* tp = tile + (kl + 16 * i) * 129 + n4 * 4;
;       tp[0] = cur[i][0]; tp[1] = cur[i][1]; tp[2] = cur[i][2]; tp[3] = cur[i][3];
;     }
;     __syncthreads();
;     {
;       const int n = tid >> 2, kg = tid & 3;
;       unsigned w[8];
; #pragma unroll
;       for (int j = 0; j < 8; ++j) w[j] = pack2bf(tile[(kg * 16 + 2 * j) * 129 + n], tile[(kg * 16 + 2 * j + 1) * 129 + n]);
;       bf16_t* dp = dst + (size_t)(n0 + n) * K + k0 + kg * 16;
;       *(u32x4*)dp = (u32x4){w[0], w[1], w[2], w[3]};
;       *(u32x4*)(dp + 8) = (u32x4){w[4], w[5], w[6], w[7]};
.LBB0_123:
	s_mov_b32 s98, s2
	s_mov_b32 s99, 352
	s_mov_b32 s100, s60
	s_mov_b64 exec, -1
	v_writelane_b32 v154, s10, 0
	v_writelane_b32 v154, s11, 1
	v_writelane_b32 v154, s12, 2
	v_writelane_b32 v154, s13, 3
	v_writelane_b32 v154, s14, 4
	v_writelane_b32 v154, s15, 5
	v_writelane_b32 v154, s16, 6
	v_writelane_b32 v154, s17, 7
	v_writelane_b32 v154, s18, 8
	v_writelane_b32 v154, s19, 9
	v_writelane_b32 v154, s20, 10
	v_writelane_b32 v154, s21, 11
	v_writelane_b32 v154, s22, 12
	v_writelane_b32 v154, s23, 13
	v_writelane_b32 v154, s24, 14
	v_writelane_b32 v154, s25, 15
	v_readlane_b32 s4, v254, 0
	v_readlane_b32 s5, v254, 1
	v_and_b32_e32 v0, 7, v228
	v_lshrrev_b32_e32 v1, 3, v228
	s_nop 1
	s_load_dwordx2 s[8:9], s[4:5], 0xe0
	s_waitcnt lgkmcnt(0)
	s_mov_b32 s17, s98
	s_mov_b32 s18, 1
	s_branch .Lcvp_dec
.Lcvp_loop:
	s_waitcnt vmcnt(16)
	v_cvt_pk_bf16_f32 v114, v50, v54
	v_cvt_pk_bf16_f32 v115, v58, v62
	v_cvt_pk_bf16_f32 v116, v66, v70
	v_cvt_pk_bf16_f32 v117, v74, v78
	v_cvt_pk_bf16_f32 v122, v51, v55
	v_cvt_pk_bf16_f32 v123, v59, v63
	v_cvt_pk_bf16_f32 v124, v67, v71
	v_cvt_pk_bf16_f32 v125, v75, v79
	v_cvt_pk_bf16_f32 v130, v52, v56
	v_cvt_pk_bf16_f32 v131, v60, v64
	v_cvt_pk_bf16_f32 v132, v68, v72
	v_cvt_pk_bf16_f32 v133, v76, v80
	v_cvt_pk_bf16_f32 v138, v53, v57
	v_cvt_pk_bf16_f32 v139, v61, v65
	v_cvt_pk_bf16_f32 v140, v69, v73
	v_cvt_pk_bf16_f32 v141, v77, v81
	s_waitcnt vmcnt(8)
	v_cvt_pk_bf16_f32 v118, v82, v86
	v_cvt_pk_bf16_f32 v119, v90, v94
	v_cvt_pk_bf16_f32 v120, v98, v102
	v_cvt_pk_bf16_f32 v121, v106, v110
	v_cvt_pk_bf16_f32 v126, v83, v87
	v_cvt_pk_bf16_f32 v127, v91, v95
	v_cvt_pk_bf16_f32 v128, v99, v103
	v_cvt_pk_bf16_f32 v129, v107, v111
	v_cvt_pk_bf16_f32 v134, v84, v88
	v_cvt_pk_bf16_f32 v135, v92, v96
	v_cvt_pk_bf16_f32 v136, v100, v104
	v_cvt_pk_bf16_f32 v137, v108, v112
	v_cvt_pk_bf16_f32 v142, v85, v89
	v_cvt_pk_bf16_f32 v143, v93, v97
	v_cvt_pk_bf16_f32 v144, v101, v105
	v_cvt_pk_bf16_f32 v145, v109, v113
	s_add_u32 s17, s98, s100
.Lcvp_dec:
	s_cmp_ge_u32 s17, s99
	s_cbranch_scc1 .Lcvp_nomore
	s_cmp_lt_u32 s17, 352
	s_cbranch_scc1 .Lcvp_seg0
	s_cmp_lt_u32 s17, 752
	s_cbranch_scc1 .Lcvp_seg1
	s_cmp_lt_u32 s17, 880
	s_cbranch_scc1 .Lcvp_seg2
	s_cmp_lt_u32 s17, 1584
	s_cbranch_scc1 .Lcvp_seg3
	s_cmp_lt_u32 s17, 1936
	s_cbranch_scc1 .Lcvp_seg4
	s_cmp_lt_u32 s17, 2640
	s_cbranch_scc1 .Lcvp_seg5
	s_cmp_lt_u32 s17, 2992
	s_cbranch_scc1 .Lcvp_seg6
	s_cmp_lt_u32 s17, 3392
	s_cbranch_scc1 .Lcvp_seg7
	s_cmp_lt_u32 s17, 3520
	s_cbranch_scc1 .Lcvp_seg8
	s_cmp_lt_u32 s17, 4224
	s_cbranch_scc1 .Lcvp_seg9
	s_branch .Lcvp_seg10
.Lcvp_seg0:
	s_sub_u32 s3, s17, 0
	s_mov_b32 s101, 0
	s_branch .Lcvp_WD
.Lcvp_seg1:
	s_sub_u32 s3, s17, 352
	s_mov_b32 s101, 0
	s_branch .Lcvp_WIN
.Lcvp_seg2:
	s_sub_u32 s3, s17, 752
	s_mov_b32 s101, 0
	s_branch .Lcvp_WOUT
.Lcvp_seg3:
	s_sub_u32 s3, s17, 880
	s_mov_b32 s101, 1
	s_branch .Lcvp_WGU
.Lcvp_seg4:
	s_sub_u32 s3, s17, 1584
	s_mov_b32 s101, 1
	s_branch .Lcvp_WD
.Lcvp_seg5:
	s_sub_u32 s3, s17, 1936
	s_mov_b32 s101, 2
	s_branch .Lcvp_WGU
.Lcvp_seg6:
	s_sub_u32 s3, s17, 2640
	s_mov_b32 s101, 2
	s_branch .Lcvp_WD
.Lcvp_seg7:
	s_sub_u32 s3, s17, 2992
	s_mov_b32 s101, 1
	s_branch .Lcvp_WIN
.Lcvp_seg8:
	s_sub_u32 s3, s17, 3392
	s_mov_b32 s101, 1
	s_branch .Lcvp_WOUT
.Lcvp_seg9:
	s_sub_u32 s3, s17, 3520
	s_mov_b32 s101, 3
	s_branch .Lcvp_WGU
.Lcvp_seg10:
	s_sub_u32 s3, s17, 4224
	s_mov_b32 s101, 3
	s_branch .Lcvp_WD
.Lcvp_WD:
	s_load_dwordx2 s[6:7], s[4:5], 0x50
	s_lshr_b32 s12, s3, 3
	s_and_b32 s13, s3, 7
	s_mul_i32 s14, s101, 0x2c00000
	s_lshl_b32 s15, s12, 20
	s_add_u32 s14, s14, s15
	s_lshl_b32 s15, s13, 10
	s_add_u32 s14, s14, s15
	s_mul_i32 s16, s101, 0x1600000
	s_add_u32 s16, s16, 0xb0bc000
	s_mul_i32 s15, s13, 0x2c0000
	s_add_u32 s16, s16, s15
	s_lshl_b32 s15, s12, 8
	s_add_u32 s16, s16, s15
	s_waitcnt lgkmcnt(0)
	s_add_u32 s6, s6, s14
	s_addc_u32 s7, s7, 0
	s_add_u32 s10, s8, s16
	s_addc_u32 s11, s9, 0
	v_lshlrev_b32_e32 v2, 16, v0
	v_lshl_add_u32 v2, v1, 4, v2
	v_mov_b32_e32 v3, 0
	v_lshl_add_u64 v[2:3], v[2:3], 0, s[6:7]
	v_mov_b32_e32 v4, 0x2000
	v_mov_b32_e32 v5, 0
	v_mul_u32_u24_e32 v156, 0xb000, v1
	v_lshl_add_u32 v156, v0, 4, v156
	v_mov_b32_e32 v157, 0
	v_lshl_add_u64 v[156:157], v[156:157], 0, s[10:11]
	v_mov_b32_e32 v158, 0x2c00
	v_mov_b32_e32 v159, 0
	s_branch .Lcvp_body
; __device__ __forceinline__ int win_src_col(int nd) {
;   if (nd < 2048) return nd;
;   if (nd < 4608) return nd + 16;
;   if (nd < 6144) return nd + 32;
;   if (nd < 6160) return nd - 6144 + 2048;
;   if (nd < 6176) return nd - 6160 + 4624;
;   return -1;
; }
; __device__ __forceinline__ void cvt_decode(PP p, int tile, const float*& src  , int& ld, bf16_t*& dst, int& K, int& k0, int& n0, int n4) {
;     ...
;   if (tile < NT_WGU) {
;     const int li = tile / (32 * 88), r = tile % (32 * 88), kt = r / 88, ntile = r % 88;
;     K = D; k0 = kt * 64; n0 = ntile * 128; ld = DFF; dst = (bf16_t*)(ws + WS_WGU) + (size_t)li * 2 * DFF * D;
;     const int pn = n0 / 256, bj = (n0 / 128) & 1;
;     const float* base = (bj ? p->ffn_wu : p->ffn_wg) + (size_t)li * D * DFF;
;     src = base + (size_t)k0 * ld + pn * 128 + n4 * 4;
;   } else if (tile < NT_WGU + NT_WD) {
;     const int t2 = tile - NT_WGU; const int li = t2 / (88 * 16), r = t2 % (88 * 16), kt = r / 16, ntile = r % 16;
;     K = DFF; k0 = kt * 64; n0 = ntile * 128; ld = D; dst = (bf16_t*)(ws + WS_WD) + (size_t)li * D * DFF;
;     src = p->ffn_wd + (size_t)li * DFF * D + (size_t)k0 * ld + n0 + n4 * 4;
;   } else if (tile < NT_WGU + NT_WD + NT_WIN) {
;     const int t2 = tile - NT_WGU - NT_WD; const int l = t2 / (32 * 50), r = t2 % (32 * 50), kt = r / 50, ntile = r % 50;
;     K = D; k0 = kt * 64; n0 = ntile * 128; ld = DIN_SRC; dst = (bf16_t*)(ws + WS_WIN) + (size_t)l * DIN * D;
;     const int sc = win_src_col(n0 + n4 * 4);
;     if (sc >= 0) src = p->w_in + (size_t)l * D * DIN_SRC + (size_t)k0 * ld + sc;
;   } else {
;     const int t2 = tile - NT_WGU - NT_WD - NT_WIN; const int l = t2 / (32 * 16), r = t2 % (32 * 16), kt = r / 16, ntile = r % 16;
;     K = D; k0 = kt * 64; n0 = ntile * 128; ld = D; dst = (bf16_t*)(ws + WS_WOUT) + (size_t)l * D * D;
;     src = p->w_out + (size_t)l * D * D + (size_t)k0 * ld + n0 + n4 * 4;
;   }
.Lcvp_WOUT:
	s_load_dwordx2 s[6:7], s[4:5], 0x60
	s_lshr_b32 s12, s3, 3
	s_and_b32 s13, s3, 7
	s_lshl_b32 s14, s101, 24
	s_lshl_b32 s15, s12, 20
	s_add_u32 s14, s14, s15
	s_lshl_b32 s15, s13, 10
	s_add_u32 s14, s14, s15
	s_lshl_b32 s16, s101, 23
	s_add_u32 s16, s16, 0x13abc000
	s_lshl_b32 s15, s13, 20
	s_add_u32 s16, s16, s15
	s_lshl_b32 s15, s12, 8
	s_add_u32 s16, s16, s15
	s_waitcnt lgkmcnt(0)
	s_add_u32 s6, s6, s14
	s_addc_u32 s7, s7, 0
	s_add_u32 s10, s8, s16
	s_addc_u32 s11, s9, 0
	v_lshlrev_b32_e32 v2, 16, v0
	v_lshl_add_u32 v2, v1, 4, v2
	v_mov_b32_e32 v3, 0
	v_lshl_add_u64 v[2:3], v[2:3], 0, s[6:7]
	v_mov_b32_e32 v4, 0x2000
	v_mov_b32_e32 v5, 0
	v_mul_u32_u24_e32 v156, 0x4000, v1
	v_lshl_add_u32 v156, v0, 4, v156
	v_mov_b32_e32 v157, 0
	v_lshl_add_u64 v[156:157], v[156:157], 0, s[10:11]
	v_mov_b32_e32 v158, 0x1000
	v_mov_b32_e32 v159, 0
	s_branch .Lcvp_body
.Lcvp_WIN:
	s_load_dwordx2 s[6:7], s[4:5], 0x58
	s_mul_i32 s12, s3, 1311
	s_lshr_b32 s12, s12, 15
	s_mul_i32 s13, s12, 25
	s_sub_u32 s13, s3, s13
	s_mul_i32 s14, s101, 0x3040000
	s_mul_i32 s15, s12, 0x304000
	s_add_u32 s14, s14, s15
	s_mul_i32 s16, s101, 0x1900000
	s_add_u32 s16, s16, 0x108bc000
	s_lshl_b32 s15, s13, 20
	s_add_u32 s16, s16, s15
	s_lshl_b32 s15, s12, 8
	s_add_u32 s16, s16, s15
	s_waitcnt lgkmcnt(0)
	s_add_u32 s6, s6, s14
	s_addc_u32 s7, s7, 0
	s_add_u32 s10, s8, s16
	s_addc_u32 s11, s9, 0
	s_lshl_b32 s15, s13, 8
	v_lshl_add_u32 v150, v1, 2, s15
	v_mov_b32_e32 v148, 0xfffff000
	v_mov_b32_e32 v149, 0xfffffa00
	v_mov_b32_e32 v147, 0
	v_cmp_le_u32_e32 vcc, 0x800, v150
	s_nop 1
	v_cndmask_b32_e64 v147, v147, 16, vcc
	v_cmp_le_u32_e32 vcc, 0x1200, v150
	s_nop 1
	v_cndmask_b32_e64 v147, v147, 32, vcc
	v_cmp_le_u32_e32 vcc, 0x1800, v150
	s_nop 1
	v_cndmask_b32_e32 v147, v147, v148, vcc
	v_cmp_le_u32_e32 vcc, 0x1810, v150
	s_nop 1
	v_cndmask_b32_e32 v147, v147, v149, vcc
	v_add_u32_e32 v147, v150, v147
	v_mul_u32_u24_e32 v2, 0x30400, v0
	v_lshl_add_u32 v2, v147, 2, v2
	v_mov_b32_e32 v3, 0
	v_lshl_add_u64 v[2:3], v[2:3], 0, s[6:7]
	v_mov_b32_e32 v4, 0x6080
	v_mov_b32_e32 v5, 0
	s_add_u32 s14, s8, 0x5000
	s_addc_u32 s15, s9, 0
	v_mov_b32_e32 v148, s14
	v_mov_b32_e32 v149, s15
	v_cmp_le_u32_e32 vcc, 0x1820, v150
	s_nop 1
	v_cndmask_b32_e32 v2, v2, v148, vcc
	v_cndmask_b32_e32 v3, v3, v149, vcc
	v_cndmask_b32_e64 v4, v4, 0, vcc
	v_mul_u32_u24_e32 v156, 0x4000, v1
	v_lshl_add_u32 v156, v0, 4, v156
	v_mov_b32_e32 v157, 0
	v_lshl_add_u64 v[156:157], v[156:157], 0, s[10:11]
	v_mov_b32_e32 v158, 0x1000
	v_mov_b32_e32 v159, 0
	s_branch .Lcvp_body
.Lcvp_WGU:
	s_load_dwordx2 s[6:7], s[4:5], 0x40
	s_load_dwordx2 s[0:1], s[4:5], 0x48
	s_mul_i32 s12, s3, 745
	s_lshr_b32 s12, s12, 15
	s_mul_i32 s13, s12, 44
	s_sub_u32 s13, s3, s13
	s_mul_i32 s14, s101, 0x2c00000
	s_mul_i32 s15, s12, 0x2c0000
	s_add_u32 s14, s14, s15
	s_lshl_b32 s15, s13, 9
	s_add_u32 s14, s14, s15
	s_mul_i32 s16, s101, 0x2c00000
	s_add_u32 s16, s16, 0xbc000
	s_lshl_b32 s15, s13, 20
	s_add_u32 s16, s16, s15
	s_lshl_b32 s15, s12, 8
	s_add_u32 s16, s16, s15
	s_waitcnt lgkmcnt(0)
	s_add_u32 s6, s6, s14
	s_addc_u32 s7, s7, 0
	s_add_u32 s0, s0, s14
	s_addc_u32 s1, s1, 0
	s_add_u32 s10, s8, s16
	s_addc_u32 s11, s9, 0
	v_mov_b32_e32 v2, s6
	v_mov_b32_e32 v3, s7
	v_mov_b32_e32 v148, s0
	v_mov_b32_e32 v149, s1
	v_cmp_le_u32_e32 vcc, 32, v1
	s_nop 1
	v_cndmask_b32_e32 v2, v2, v148, vcc
	v_cndmask_b32_e32 v3, v3, v149, vcc
	v_and_b32_e32 v147, 31, v1
	v_mul_u32_u24_e32 v150, 0x2c000, v0
	v_lshl_add_u32 v150, v147, 4, v150
	v_mov_b32_e32 v151, 0
	v_lshl_add_u64 v[2:3], v[2:3], 0, v[150:151]
	v_mov_b32_e32 v4, 0x5800
	v_mov_b32_e32 v5, 0
	v_mul_u32_u24_e32 v156, 0x4000, v1
	v_lshl_add_u32 v156, v0, 4, v156
	v_mov_b32_e32 v157, 0
	v_lshl_add_u64 v[156:157], v[156:157], 0, s[10:11]
	v_mov_b32_e32 v158, 0x1000
	v_mov_b32_e32 v159, 0

; __device__ __forceinline__ int ltid() { int t = __builtin_amdgcn_workitem_id_x(); asm volatile("" : "+v"(t)); return t; }
; __device__ __forceinline__ unsigned xb_ld(unsigned* p)              { return __hip_atomic_load(p, __ATOMIC_RELAXED, __HIP_MEMORY_SCOPE_AGENT); }
; __device__ __forceinline__ unsigned xb_add(unsigned* p, unsigned v) { return __hip_atomic_fetch_add(p, v, __ATOMIC_RELAXED, __HIP_MEMORY_SCOPE_AGENT); }
; __device__ void phase_convert(PP p, unsigned char* smem) {
;     ...
;       bf16_t* dp = dst + (size_t)(n0 + n) * K + k0 + kg * 16;
;       *(u32x4*)dp = (u32x4){w[0], w[1], w[2], w[3]};
;       *(u32x4*)(dp + 8) = (u32x4){w[4], w[5], w[6], w[7]};
; __device__ __forceinline__ void xcd_barrier_complete(unsigned* bar, unsigned x, unsigned& nloc, unsigned& nx) {
;     const unsigned G = gridDim.x * gridDim.y * gridDim.z;
;     unsigned sum, cnt, mine, sp = 0u;
;     for (;;) {
;         sum = 0u; cnt = 0u; mine = 0u;
; #pragma unroll
;         for (unsigned j = 0; j < 16; ++j) { const unsigned c = xb_ld(&bar[XB_XCNT(j)]); sum += c; cnt += (c > 0u) ? 1u : 0u; mine = (j == x) ? c : mine; }
;         if (sum == G) break;
;         __builtin_amdgcn_s_sleep(1);
;         if ((++sp & 255u) == 0u) { if (xb_ld(&bar[XB_TMO])) break; if (sp > XB_SPIN_CAP) { atomicAdd(&bar[XB_TMO], 1u); break; } }
;     }
;     nloc = mine > 0u ? mine : 1u; nx = cnt > 0u ? cnt : 1u;
; }
; __device__ __forceinline__ void xcd_barrier(const XcdBarrier& b) {
;     asm volatile("s_waitcnt vmcnt(0)" ::: "memory");
;     __syncthreads();
;     if (ltid() == 0) {
;         unsigned* bar = b.bar;
;         __builtin_amdgcn_s_waitcnt(0);
;         unsigned nloc = b.st[0], nx = b.st[1];
;         if (nloc == 0u) { xcd_barrier_complete(bar, b.x, nloc, nx); b.st[0] = nloc; b.st[1] = nx; }
;         const unsigned old = xb_add(&bar[XB_XSUB(b.x)], 1u);
.Lcvp_nomore:
	s_cmp_eq_u32 s18, 0
	s_cbranch_scc1 .Lcvp_st
	s_mov_b32 s18, 0
	s_waitcnt vmcnt(0)
	s_branch .Lcvp_afterst
.Lcvp_st:
	global_store_dwordx4 v[6:7], v[114:117], off
	global_store_dwordx4 v[6:7], v[118:121], off offset:128
	v_lshl_add_u64 v[6:7], v[6:7], 0, v[8:9]
	global_store_dwordx4 v[6:7], v[122:125], off
	global_store_dwordx4 v[6:7], v[126:129], off offset:128
	v_lshl_add_u64 v[6:7], v[6:7], 0, v[8:9]
	global_store_dwordx4 v[6:7], v[130:133], off
	global_store_dwordx4 v[6:7], v[134:137], off offset:128
	v_lshl_add_u64 v[6:7], v[6:7], 0, v[8:9]
	global_store_dwordx4 v[6:7], v[138:141], off
	global_store_dwordx4 v[6:7], v[142:145], off offset:128
.Lcvp_afterst:
	v_mov_b32_e32 v6, v156
	v_mov_b32_e32 v7, v157
	v_mov_b32_e32 v8, v158
	v_mov_b32_e32 v9, v159
	s_mov_b32 s98, s17
	s_cmp_lt_u32 s98, s99
	s_cbranch_scc1 .Lcvp_loop
.Lcvp_done:
	s_waitcnt vmcnt(0)
	v_readlane_b32 s10, v154, 0
	v_readlane_b32 s11, v154, 1
	v_readlane_b32 s12, v154, 2
	v_readlane_b32 s13, v154, 3
	v_readlane_b32 s14, v154, 4
	v_readlane_b32 s15, v154, 5
	v_readlane_b32 s16, v154, 6
	v_readlane_b32 s17, v154, 7
	v_readlane_b32 s18, v154, 8
	v_readlane_b32 s19, v154, 9
	v_readlane_b32 s20, v154, 10
	v_readlane_b32 s21, v154, 11
	v_readlane_b32 s22, v154, 12
	v_readlane_b32 s23, v154, 13
	v_readlane_b32 s24, v154, 14
	v_readlane_b32 s25, v154, 15
	s_nop 4
	v_readlane_b32 s4, v254, 0
	v_readlane_b32 s5, v254, 1
	s_getreg_b32 s3, hwreg(HW_REG_XCC_ID, 0, 4)
	s_waitcnt vmcnt(0)
	v_mov_b32_e32 v0, v228
	s_barrier
	s_nop 0
	v_cmp_eq_u32_e32 vcc, 0, v0
	s_and_saveexec_b64 s[0:1], vcc
	s_cbranch_execz .LBB0_175
	s_add_i32 s6, 0, 0x23410
	v_mov_b32_e32 v0, s6
	s_load_dwordx2 s[4:5], s[4:5], 0xe0
	s_waitcnt vmcnt(0) expcnt(0) lgkmcnt(0)
	ds_read_b32 v2, v0
	s_add_i32 s6, 0, 0x23414
	v_mov_b32_e32 v0, s6
	ds_read_b32 v0, v0
	s_and_b32 s3, s3, 15
	s_waitcnt lgkmcnt(1)
	v_cmp_ne_u32_e32 vcc, 0, v2
	s_cbranch_vccnz .LBB0_139
	s_add_u32 s6, s4, 0x1200
	s_addc_u32 s7, s5, 0
	s_add_u32 s8, s4, 0x1400
	s_addc_u32 s9, s5, 0
	s_add_u32 s10, s4, 0x1500
	s_addc_u32 s11, s5, 0
	s_add_u32 s12, s4, 0x1600
	s_addc_u32 s13, s5, 0
	s_add_u32 s14, s4, 0x1700
	s_addc_u32 s15, s5, 0
	s_add_u32 s16, s4, 0x1800
	s_addc_u32 s17, s5, 0
	s_add_u32 s18, s4, 0x1900
	s_addc_u32 s19, s5, 0
	s_add_u32 s20, s4, 0x1a00
	s_addc_u32 s21, s5, 0
	s_add_u32 s22, s4, 0x1b00
	s_addc_u32 s23, s5, 0
	s_add_u32 s24, s4, 0x1c00
	s_addc_u32 s25, s5, 0
	s_add_u32 s26, s4, 0x1d00
	s_addc_u32 s27, s5, 0
	s_add_u32 s28, s4, 0x1e00
	s_addc_u32 s29, s5, 0
	s_add_u32 s30, s4, 0x1f00
	s_addc_u32 s31, s5, 0
	s_add_u32 s34, s4, 0x2000
	s_addc_u32 s35, s5, 0
	s_add_u32 s36, s4, 0x2100
	s_addc_u32 s37, s5, 0
	s_add_u32 s38, s4, 0x2200
	s_addc_u32 s39, s5, 0
	s_mul_i32 s33, s61, s48
	s_add_u32 s40, s4, 0x2300
	s_mul_i32 s33, s33, s60
	s_addc_u32 s41, s5, 0
	s_mov_b32 s49, 1
	v_mov_b32_e32 v16, 0
	s_branch .LBB0_127

; __device__ void phase_convert(PP p, unsigned char* smem) {
;     ...
;   int t = blockIdx.x;
;   if (t < NT_ALL) {
;     cvt_decode(p, t, src, ld, dst, K, k0, n0, n4);
; #pragma unroll
;     for (int i = 0; i < 4; ++i) cur[i] = src ? *(const f32x4*)(src + (size_t)(kl + 16 * i) * ld) : (f32x4){0.f, 0.f, 0.f, 0.f};
;   }
;   for (; t < NT_ALL; t += gridDim.x) {
;     const int tn = t + gridDim.x;
;     const float* src2 = nullptr; int ld2 = 0, K2, k02, n02; bf16_t* dst2;
.LBB0_667:
	s_cmp_eq_u32 s51, 0
	s_cbranch_scc1 .Lcvt_t0
	s_cmp_eq_u32 s51, 1
	s_cbranch_scc1 .Lcvt_t1
	s_cmp_eq_u32 s51, 3
	s_cbranch_scc1 .Lcvt_t3
	s_cmp_eq_u32 s51, 7
	s_cbranch_scc1 .Lcvt_t7
	s_cmp_eq_u32 s51, 9
	s_cbranch_scc1 .Lcvt_t9
	s_cmp_eq_u32 s51, 10
	s_cbranch_scc1 .Lcvt_t10
	s_cmp_eq_u32 s51, 12
	s_cbranch_scc1 .Lcvt_t12
	s_cmp_eq_u32 s51, 13
	s_cbranch_scc1 .Lcvt_t13
	s_cmp_eq_u32 s51, 15
	s_cbranch_scc1 .Lcvt_t15
	s_cmp_eq_u32 s51, 21
	s_cbranch_scc1 .Lcvt_t21
	s_branch .Lcvt_skip
.Lcvt_t0:
	s_mov_b32 s98, 352
	s_mov_b32 s99, 832
	s_mov_b32 s100, 48
	s_branch .Lcvt_go
.Lcvt_t1:
	s_mov_b32 s98, 832
	s_mov_b32 s99, 1152
	s_mov_b32 s100, 128
	s_branch .Lcvt_go
.Lcvt_t3:
	s_mov_b32 s98, 1152
	s_mov_b32 s99, 1824
	s_mov_b32 s100, 132
	s_branch .Lcvt_go
.Lcvt_t7:
	s_mov_b32 s98, 1824
	s_mov_b32 s99, 1952
	s_mov_b32 s100, 128
	s_branch .Lcvt_go
.Lcvt_t9:
	s_mov_b32 s98, 1952
	s_mov_b32 s99, 2432
	s_mov_b32 s100, 48
	s_branch .Lcvt_go
.Lcvt_t10:
	s_mov_b32 s98, 2432
	s_mov_b32 s99, 2752
	s_mov_b32 s100, 128
	s_branch .Lcvt_go
.Lcvt_t12:
	s_mov_b32 s98, 2752
	s_mov_b32 s99, 3232
	s_mov_b32 s100, 48
	s_branch .Lcvt_go
.Lcvt_t13:
	s_mov_b32 s98, 3232
	s_mov_b32 s99, 3552
	s_mov_b32 s100, 128
	s_branch .Lcvt_go
.Lcvt_t15:
	s_mov_b32 s98, 3552
	s_mov_b32 s99, 4224
	s_mov_b32 s100, 132
	s_branch .Lcvt_go
.Lcvt_t21:
	s_mov_b32 s98, 4224
	s_mov_b32 s99, 4576
	s_mov_b32 s100, 128
	s_branch .Lcvt_go
.Lcvt_go:
	s_cmp_lt_u32 s2, s100
	s_cbranch_scc1 .Lcvt_skip
	s_sub_u32 s3, s2, s100
	s_add_u32 s98, s98, s3
	s_sub_u32 s100, s60, s100
	s_mov_b64 exec, -1
	v_writelane_b32 v154, s10, 0
	v_writelane_b32 v154, s11, 1
	v_writelane_b32 v154, s12, 2
	v_writelane_b32 v154, s13, 3
	v_writelane_b32 v154, s14, 4
	v_writelane_b32 v154, s15, 5
	v_writelane_b32 v154, s16, 6
	v_writelane_b32 v154, s17, 7
	v_writelane_b32 v154, s18, 8
	v_writelane_b32 v154, s19, 9
	v_writelane_b32 v154, s20, 10
	v_writelane_b32 v154, s21, 11
	v_writelane_b32 v154, s22, 12
	v_writelane_b32 v154, s23, 13
	v_writelane_b32 v154, s24, 14
	v_writelane_b32 v154, s25, 15
	v_readlane_b32 s4, v254, 0
	v_readlane_b32 s5, v254, 1
	v_and_b32_e32 v0, 7, v228
	v_lshrrev_b32_e32 v1, 3, v228
	s_nop 1
	s_load_dwordx2 s[8:9], s[4:5], 0xe0
	s_waitcnt lgkmcnt(0)
	s_mov_b32 s17, s98
	s_mov_b32 s18, 1
	s_branch .Lcvt_dec
